# GEMM K-loops: static s_setprio 1 on waves 0-3 instead of waves 4-7 (per-segment flips removed)
# baseline (speedup 1.0000x reference)
; template <class Epi>
; __device__ __forceinline__ void gemm_phase(LAS unsigned char* lds, const Gemm g, const StaticOrder& S, const Epi& E) {
;     ...
;     Unit cur, nxt; int ui = 0;
;     if (!S.next(0, cur)) return;
;     f32x4 acc[2][2][4][2];
; #pragma unroll
;     for (int a = 0; a < 2; ++a)
; #pragma unroll
;         for (int b = 0; b < 2; ++b)
; #pragma unroll
;             for (int m = 0; m < 4; ++m)
; #pragma unroll
;                 for (int n = 0; n < 2; ++n) acc[a][b][m][n] = (f32x4){0.f, 0.f, 0.f, 0.f};
.Lp7_units_done:
	s_add_u32 s44, s18, 0x100
	v_mov_b32_e32 v4, 0
	s_addc_u32 s46, s19, 0
	s_cmp_eq_u32 s40, 1
	s_cselect_b32 s47, -2, 64
	s_waitcnt lgkmcnt(0)
	v_mov_b32_e32 v5, v4
	v_mov_b32_e32 v6, v4
	v_mov_b32_e32 v7, v4
	v_mov_b32_e32 v8, v4
	v_mov_b32_e32 v9, v4
	v_mov_b32_e32 v10, v4
	v_mov_b32_e32 v11, v4
	v_mov_b32_e32 v20, v4
	v_mov_b32_e32 v21, v4
	v_mov_b32_e32 v22, v4
	v_mov_b32_e32 v23, v4
	v_mov_b32_e32 v24, v4
	v_mov_b32_e32 v25, v4
	v_mov_b32_e32 v26, v4
	v_mov_b32_e32 v27, v4
	v_mov_b32_e32 v36, v4
	v_mov_b32_e32 v37, v4
	v_mov_b32_e32 v38, v4
	v_mov_b32_e32 v39, v4
	v_mov_b32_e32 v40, v4
	v_mov_b32_e32 v41, v4
	v_mov_b32_e32 v42, v4
	v_mov_b32_e32 v43, v4
	v_mov_b32_e32 v52, v4
	v_mov_b32_e32 v53, v4
	v_mov_b32_e32 v54, v4
	v_mov_b32_e32 v55, v4
	v_mov_b32_e32 v56, v4
	v_mov_b32_e32 v57, v4
	v_mov_b32_e32 v58, v4
	v_mov_b32_e32 v59, v4
	v_mov_b32_e32 v12, v4
	v_mov_b32_e32 v13, v4
	v_mov_b32_e32 v14, v4
	v_mov_b32_e32 v15, v4
	v_mov_b32_e32 v16, v4
	v_mov_b32_e32 v17, v4
	v_mov_b32_e32 v18, v4
	v_mov_b32_e32 v19, v4
	v_mov_b32_e32 v28, v4
	v_mov_b32_e32 v29, v4
	v_mov_b32_e32 v30, v4
	v_mov_b32_e32 v31, v4
	v_mov_b32_e32 v32, v4
	v_mov_b32_e32 v33, v4
	v_mov_b32_e32 v34, v4
	v_mov_b32_e32 v35, v4
	v_mov_b32_e32 v44, v4
	v_mov_b32_e32 v45, v4
	v_mov_b32_e32 v46, v4
	v_mov_b32_e32 v47, v4
	v_mov_b32_e32 v48, v4
	v_mov_b32_e32 v49, v4
	v_mov_b32_e32 v50, v4
	v_mov_b32_e32 v51, v4
	v_mov_b32_e32 v60, v4
	v_mov_b32_e32 v61, v4
	v_mov_b32_e32 v62, v4
	v_mov_b32_e32 v63, v4
	v_mov_b32_e32 v64, v4
	v_mov_b32_e32 v65, v4
	v_mov_b32_e32 v66, v4
	v_mov_b32_e32 v67, v4
	v_mov_b32_e32 v68, v4
	v_mov_b32_e32 v69, v4
	v_mov_b32_e32 v70, v4
	v_mov_b32_e32 v71, v4
	v_mov_b32_e32 v72, v4
	v_mov_b32_e32 v73, v4
	v_mov_b32_e32 v74, v4
	v_mov_b32_e32 v75, v4
	v_mov_b32_e32 v84, v4
	v_mov_b32_e32 v85, v4
	v_mov_b32_e32 v86, v4
	v_mov_b32_e32 v87, v4
	v_mov_b32_e32 v88, v4
	v_mov_b32_e32 v89, v4
	v_mov_b32_e32 v90, v4
	v_mov_b32_e32 v91, v4
	v_mov_b32_e32 v100, v4
	v_mov_b32_e32 v101, v4
	v_mov_b32_e32 v102, v4
	v_mov_b32_e32 v103, v4
	v_mov_b32_e32 v104, v4
	v_mov_b32_e32 v105, v4
	v_mov_b32_e32 v106, v4
	v_mov_b32_e32 v107, v4
	v_mov_b32_e32 v116, v4
	v_mov_b32_e32 v117, v4
	v_mov_b32_e32 v118, v4
	v_mov_b32_e32 v119, v4
	v_mov_b32_e32 v120, v4
	v_mov_b32_e32 v121, v4
	v_mov_b32_e32 v122, v4
	v_mov_b32_e32 v123, v4
	v_mov_b32_e32 v76, v4
	v_mov_b32_e32 v77, v4
	v_mov_b32_e32 v78, v4
	v_mov_b32_e32 v79, v4
	v_mov_b32_e32 v80, v4
	v_mov_b32_e32 v81, v4
	v_mov_b32_e32 v82, v4
	v_mov_b32_e32 v83, v4
	v_mov_b32_e32 v92, v4
	v_mov_b32_e32 v93, v4
	v_mov_b32_e32 v94, v4
	v_mov_b32_e32 v95, v4
	v_mov_b32_e32 v96, v4
	v_mov_b32_e32 v97, v4
	v_mov_b32_e32 v98, v4
	v_mov_b32_e32 v99, v4
	v_mov_b32_e32 v108, v4
	v_mov_b32_e32 v109, v4
	v_mov_b32_e32 v110, v4
	v_mov_b32_e32 v111, v4
	v_mov_b32_e32 v112, v4
	v_mov_b32_e32 v113, v4
	v_mov_b32_e32 v114, v4
	v_mov_b32_e32 v115, v4
	v_mov_b32_e32 v124, v4
	v_mov_b32_e32 v125, v4
	v_mov_b32_e32 v126, v4
	v_mov_b32_e32 v127, v4
	v_mov_b32_e32 v128, v4
	v_mov_b32_e32 v129, v4
	v_mov_b32_e32 v130, v4
	v_mov_b32_e32 v131, v4
	v_readfirstlane_b32 s98, v151
	s_nop 3
	s_lshr_b32 s98, s98, 8
	s_cmp_lg_u32 s98, 0
	s_cbranch_scc1 .Lprio_skip_23
	s_setprio 1

; template <class Epi>
; __device__ __forceinline__ void gemm_phase(LAS unsigned char* lds, const Gemm g, const StaticOrder& S, const Epi& E) {
;     ...
; #pragma unroll
;         for (int a = 0; a < 2; ++a)
; #pragma unroll
;             for (int b = 0; b < 2; ++b)
; #pragma unroll
;                 for (int m = 0; m < 4; ++m)
; #pragma unroll
;                     for (int n = 0; n < 2; ++n) acc[a][b][m][n] = (f32x4){0.f, 0.f, 0.f, 0.f};
;         cur = nxt; cA = nA; cB = nB; ++ui;
.LBB0_97:
	s_ashr_i32 s13, s12, 31
	s_cmp_ge_i32 s14, 0
	s_cselect_b64 vcc, -1, 0
	s_lshl_b64 s[14:15], s[12:13], 20
	s_add_u32 s14, s29, s14
	s_addc_u32 s15, s30, s15
	s_and_b64 s[16:17], vcc, exec
	s_cselect_b32 s13, s15, s21
	s_cselect_b32 s42, s14, s20
	s_ashr_i32 s9, s8, 31
	s_lshl_b64 s[16:17], s[8:9], 20
	s_add_u32 s16, s2, s16
	s_addc_u32 s17, s3, s17
	s_and_b64 s[24:25], vcc, exec
	s_cselect_b32 s9, s17, s23
	s_cselect_b32 s43, s16, s22
	s_add_u32 s20, s20, 0x80080
	s_addc_u32 s21, s21, 0
	s_add_u32 s44, s22, 0x100
	v_mov_b32_e32 v4, 0
	s_addc_u32 s46, s23, 0
	s_mov_b32 s47, -2
	v_mov_b32_e32 v5, v4
	v_mov_b32_e32 v6, v4
	v_mov_b32_e32 v7, v4
	v_mov_b32_e32 v8, v4
	v_mov_b32_e32 v9, v4
	v_mov_b32_e32 v10, v4
	v_mov_b32_e32 v11, v4
	v_mov_b32_e32 v20, v4
	v_mov_b32_e32 v21, v4
	v_mov_b32_e32 v22, v4
	v_mov_b32_e32 v23, v4
	v_mov_b32_e32 v24, v4
	v_mov_b32_e32 v25, v4
	v_mov_b32_e32 v26, v4
	v_mov_b32_e32 v27, v4
	v_mov_b32_e32 v36, v4
	v_mov_b32_e32 v37, v4
	v_mov_b32_e32 v38, v4
	v_mov_b32_e32 v39, v4
	v_mov_b32_e32 v40, v4
	v_mov_b32_e32 v41, v4
	v_mov_b32_e32 v42, v4
	v_mov_b32_e32 v43, v4
	v_mov_b32_e32 v52, v4
	v_mov_b32_e32 v53, v4
	v_mov_b32_e32 v54, v4
	v_mov_b32_e32 v55, v4
	v_mov_b32_e32 v56, v4
	v_mov_b32_e32 v57, v4
	v_mov_b32_e32 v58, v4
	v_mov_b32_e32 v59, v4
	v_mov_b32_e32 v12, v4
	v_mov_b32_e32 v13, v4
	v_mov_b32_e32 v14, v4
	v_mov_b32_e32 v15, v4
	v_mov_b32_e32 v16, v4
	v_mov_b32_e32 v17, v4
	v_mov_b32_e32 v18, v4
	v_mov_b32_e32 v19, v4
	v_mov_b32_e32 v28, v4
	v_mov_b32_e32 v29, v4
	v_mov_b32_e32 v30, v4
	v_mov_b32_e32 v31, v4
	v_mov_b32_e32 v32, v4
	v_mov_b32_e32 v33, v4
	v_mov_b32_e32 v34, v4
	v_mov_b32_e32 v35, v4
	v_mov_b32_e32 v44, v4
	v_mov_b32_e32 v45, v4
	v_mov_b32_e32 v46, v4
	v_mov_b32_e32 v47, v4
	v_mov_b32_e32 v48, v4
	v_mov_b32_e32 v49, v4
	v_mov_b32_e32 v50, v4
	v_mov_b32_e32 v51, v4
	v_mov_b32_e32 v60, v4
	v_mov_b32_e32 v61, v4
	v_mov_b32_e32 v62, v4
	v_mov_b32_e32 v63, v4
	v_mov_b32_e32 v64, v4
	v_mov_b32_e32 v65, v4
	v_mov_b32_e32 v66, v4
	v_mov_b32_e32 v67, v4
	v_mov_b32_e32 v68, v4
	v_mov_b32_e32 v69, v4
	v_mov_b32_e32 v70, v4
	v_mov_b32_e32 v71, v4
	v_mov_b32_e32 v72, v4
	v_mov_b32_e32 v73, v4
	v_mov_b32_e32 v74, v4
	v_mov_b32_e32 v75, v4
	v_mov_b32_e32 v84, v4
	v_mov_b32_e32 v85, v4
	v_mov_b32_e32 v86, v4
	v_mov_b32_e32 v87, v4
	v_mov_b32_e32 v88, v4
	v_mov_b32_e32 v89, v4
	v_mov_b32_e32 v90, v4
	v_mov_b32_e32 v91, v4
	v_mov_b32_e32 v100, v4
	v_mov_b32_e32 v101, v4
	v_mov_b32_e32 v102, v4
	v_mov_b32_e32 v103, v4
	v_mov_b32_e32 v104, v4
	v_mov_b32_e32 v105, v4
	v_mov_b32_e32 v106, v4
	v_mov_b32_e32 v107, v4
	v_mov_b32_e32 v116, v4
	v_mov_b32_e32 v117, v4
	v_mov_b32_e32 v118, v4
	v_mov_b32_e32 v119, v4
	v_mov_b32_e32 v120, v4
	v_mov_b32_e32 v121, v4
	v_mov_b32_e32 v122, v4
	v_mov_b32_e32 v123, v4
	v_mov_b32_e32 v76, v4
	v_mov_b32_e32 v77, v4
	v_mov_b32_e32 v78, v4
	v_mov_b32_e32 v79, v4
	v_mov_b32_e32 v80, v4
	v_mov_b32_e32 v81, v4
	v_mov_b32_e32 v82, v4
	v_mov_b32_e32 v83, v4
	v_mov_b32_e32 v92, v4
	v_mov_b32_e32 v93, v4
	v_mov_b32_e32 v94, v4
	v_mov_b32_e32 v95, v4
	v_mov_b32_e32 v96, v4
	v_mov_b32_e32 v97, v4
	v_mov_b32_e32 v98, v4
	v_mov_b32_e32 v99, v4
	v_mov_b32_e32 v108, v4
	v_mov_b32_e32 v109, v4
	v_mov_b32_e32 v110, v4
	v_mov_b32_e32 v111, v4
	v_mov_b32_e32 v112, v4
	v_mov_b32_e32 v113, v4
	v_mov_b32_e32 v114, v4
	v_mov_b32_e32 v115, v4
	v_mov_b32_e32 v124, v4
	v_mov_b32_e32 v125, v4
	v_mov_b32_e32 v126, v4
	v_mov_b32_e32 v127, v4
	v_mov_b32_e32 v128, v4
	v_mov_b32_e32 v129, v4
	v_mov_b32_e32 v130, v4
	v_mov_b32_e32 v131, v4
	v_readfirstlane_b32 s98, v151
	s_nop 3
	s_lshr_b32 s98, s98, 8
	s_cmp_lg_u32 s98, 0
	s_cbranch_scc1 .Lprio_skip_98
	s_setprio 1

; template <class Epi>
; __device__ __forceinline__ void gemm_phase(LAS unsigned char* lds, const Gemm g, const StaticOrder& S, const Epi& E) {
;     ...
; #pragma unroll
;         for (int a = 0; a < 2; ++a)
; #pragma unroll
;             for (int b = 0; b < 2; ++b)
; #pragma unroll
;                 for (int m = 0; m < 4; ++m)
; #pragma unroll
;                     for (int n = 0; n < 2; ++n) acc[a][b][m][n] = (f32x4){0.f, 0.f, 0.f, 0.f};
;         cur = nxt; cA = nA; cB = nB; ++ui;
.LBB0_216:
	s_ashr_i32 s17, s16, 31
	v_cmp_lt_i64_e32 vcc, s[18:19], v[154:155]
	s_lshl_b64 s[18:19], s[16:17], 21
	s_add_u32 s18, s37, s18
	s_addc_u32 s19, s38, s19
	s_and_b64 s[20:21], vcc, exec
	s_cselect_b32 s17, s19, s27
	s_cselect_b32 s23, s18, s26
	s_ashr_i32 s15, s14, 31
	s_lshl_b64 s[20:21], s[14:15], 21
	s_add_u32 s20, s2, s20
	s_addc_u32 s21, s3, s21
	s_and_b64 s[30:31], vcc, exec
	s_cselect_b32 s15, s21, s29
	s_cselect_b32 s25, s20, s28
	s_add_u32 s26, s26, 0x100080
	s_addc_u32 s27, s27, 0
	s_add_u32 s54, s28, 0x100
	v_mov_b32_e32 v4, 0
	s_addc_u32 s72, s29, 0
	s_mov_b32 s73, -2
	s_waitcnt lgkmcnt(0)
	v_mov_b32_e32 v5, v4
	v_mov_b32_e32 v6, v4
	v_mov_b32_e32 v7, v4
	v_mov_b32_e32 v8, v4
	v_mov_b32_e32 v9, v4
	v_mov_b32_e32 v10, v4
	v_mov_b32_e32 v11, v4
	v_mov_b32_e32 v20, v4
	v_mov_b32_e32 v21, v4
	v_mov_b32_e32 v22, v4
	v_mov_b32_e32 v23, v4
	v_mov_b32_e32 v24, v4
	v_mov_b32_e32 v25, v4
	v_mov_b32_e32 v26, v4
	v_mov_b32_e32 v27, v4
	v_mov_b32_e32 v36, v4
	v_mov_b32_e32 v37, v4
	v_mov_b32_e32 v38, v4
	v_mov_b32_e32 v39, v4
	v_mov_b32_e32 v40, v4
	v_mov_b32_e32 v41, v4
	v_mov_b32_e32 v42, v4
	v_mov_b32_e32 v43, v4
	v_mov_b32_e32 v68, v4
	v_mov_b32_e32 v69, v4
	v_mov_b32_e32 v70, v4
	v_mov_b32_e32 v71, v4
	v_mov_b32_e32 v72, v4
	v_mov_b32_e32 v73, v4
	v_mov_b32_e32 v74, v4
	v_mov_b32_e32 v75, v4
	v_mov_b32_e32 v12, v4
	v_mov_b32_e32 v13, v4
	v_mov_b32_e32 v14, v4
	v_mov_b32_e32 v15, v4
	v_mov_b32_e32 v16, v4
	v_mov_b32_e32 v17, v4
	v_mov_b32_e32 v18, v4
	v_mov_b32_e32 v19, v4
	v_mov_b32_e32 v28, v4
	v_mov_b32_e32 v29, v4
	v_mov_b32_e32 v30, v4
	v_mov_b32_e32 v31, v4
	v_mov_b32_e32 v32, v4
	v_mov_b32_e32 v33, v4
	v_mov_b32_e32 v34, v4
	v_mov_b32_e32 v35, v4
	v_mov_b32_e32 v44, v4
	v_mov_b32_e32 v45, v4
	v_mov_b32_e32 v46, v4
	v_mov_b32_e32 v47, v4
	v_mov_b32_e32 v48, v4
	v_mov_b32_e32 v49, v4
	v_mov_b32_e32 v50, v4
	v_mov_b32_e32 v51, v4
	v_mov_b32_e32 v76, v4
	v_mov_b32_e32 v77, v4
	v_mov_b32_e32 v78, v4
	v_mov_b32_e32 v79, v4
	v_mov_b32_e32 v80, v4
	v_mov_b32_e32 v81, v4
	v_mov_b32_e32 v82, v4
	v_mov_b32_e32 v83, v4
	v_mov_b32_e32 v84, v4
	v_mov_b32_e32 v85, v4
	v_mov_b32_e32 v86, v4
	v_mov_b32_e32 v87, v4
	v_mov_b32_e32 v88, v4
	v_mov_b32_e32 v89, v4
	v_mov_b32_e32 v90, v4
	v_mov_b32_e32 v91, v4
	v_mov_b32_e32 v100, v4
	v_mov_b32_e32 v101, v4
	v_mov_b32_e32 v102, v4
	v_mov_b32_e32 v103, v4
	v_mov_b32_e32 v104, v4
	v_mov_b32_e32 v105, v4
	v_mov_b32_e32 v106, v4
	v_mov_b32_e32 v107, v4
	v_mov_b32_e32 v116, v4
	v_mov_b32_e32 v117, v4
	v_mov_b32_e32 v118, v4
	v_mov_b32_e32 v119, v4
	v_mov_b32_e32 v120, v4
	v_mov_b32_e32 v121, v4
	v_mov_b32_e32 v122, v4
	v_mov_b32_e32 v123, v4
	v_mov_b32_e32 v132, v4
	v_mov_b32_e32 v133, v4
	v_mov_b32_e32 v134, v4
	v_mov_b32_e32 v135, v4
	v_mov_b32_e32 v136, v4
	v_mov_b32_e32 v137, v4
	v_mov_b32_e32 v138, v4
	v_mov_b32_e32 v139, v4
	v_mov_b32_e32 v92, v4
	v_mov_b32_e32 v93, v4
	v_mov_b32_e32 v94, v4
	v_mov_b32_e32 v95, v4
	v_mov_b32_e32 v96, v4
	v_mov_b32_e32 v97, v4
	v_mov_b32_e32 v98, v4
	v_mov_b32_e32 v99, v4
	v_mov_b32_e32 v108, v4
	v_mov_b32_e32 v109, v4
	v_mov_b32_e32 v110, v4
	v_mov_b32_e32 v111, v4
	v_mov_b32_e32 v112, v4
	v_mov_b32_e32 v113, v4
	v_mov_b32_e32 v114, v4
	v_mov_b32_e32 v115, v4
	v_mov_b32_e32 v124, v4
	v_mov_b32_e32 v125, v4
	v_mov_b32_e32 v126, v4
	v_mov_b32_e32 v127, v4
	v_mov_b32_e32 v128, v4
	v_mov_b32_e32 v129, v4
	v_mov_b32_e32 v130, v4
	v_mov_b32_e32 v131, v4
	v_mov_b32_e32 v140, v4
	v_mov_b32_e32 v141, v4
	v_mov_b32_e32 v142, v4
	v_mov_b32_e32 v143, v4
	v_mov_b32_e32 v144, v4
	v_mov_b32_e32 v145, v4
	v_mov_b32_e32 v146, v4
	v_mov_b32_e32 v147, v4
	v_readfirstlane_b32 s98, v151
	s_nop 3
	s_lshr_b32 s98, s98, 8
	s_cmp_lg_u32 s98, 0
	s_cbranch_scc1 .Lprio_skip_217
	s_setprio 1

; template <class Epi>
; __device__ __forceinline__ void gemm_phase(LAS unsigned char* lds, const Gemm g, const StaticOrder& S, const Epi& E) {
;     ...
;         const bool has_next = S.next(ui + 1, nxt);
;         const char* nA = has_next ? (const char*)g.A + (size_t)nxt.pm * tstep : cA; const char* nB = has_next ? (const char*)g.Bt + (size_t)nxt.pn * tstep : cB;
;         for (int t = 0; t < nt; t += 2) {
;             const bool last = (t == nt - 2);
;             const char* a1 = cA + (size_t)(t + 1) * kstep;
;             const char* a2 = last ? nA : cA + (size_t)(t + 2) * kstep; const char* b2 = last ? nB : cB + (size_t)(t + 2) * kstep;
;             const char* a3 = a2 + kstep; const char* b3 = b2 + kstep;
;     ...
; #pragma unroll
;         for (int a = 0; a < 2; ++a)
; #pragma unroll
;             for (int b = 0; b < 2; ++b)
; #pragma unroll
;                 for (int m = 0; m < 4; ++m)
; #pragma unroll
;                     for (int n = 0; n < 2; ++n) acc[a][b][m][n] = (f32x4){0.f, 0.f, 0.f, 0.f};
;         cur = nxt; cA = nA; cB = nB; ++ui;
.LBB0_757:
	s_ashr_i32 s15, s14, 31
	v_cmp_lt_i64_e32 vcc, s[16:17], v[168:169]
	s_lshl_b64 s[16:17], s[14:15], 20
	s_add_u32 s16, s28, s16
	s_addc_u32 s17, s29, s17
	s_and_b64 s[18:19], vcc, exec
	s_cselect_b32 s15, s17, s21
	s_cselect_b32 s42, s16, s20
	s_ashr_i32 s13, s12, 31
	s_lshl_b64 s[18:19], s[12:13], 20
	s_add_u32 s18, s82, s18
	s_addc_u32 s19, s83, s19
	s_and_b64 s[24:25], vcc, exec
	s_cselect_b32 s13, s19, s23
	s_cselect_b32 s43, s18, s22
	s_add_u32 s20, s20, 0x80080
	s_addc_u32 s21, s21, 0
	s_add_u32 s44, s22, 0x100
	v_mov_b32_e32 v4, 0
	s_addc_u32 s46, s23, 0
	s_mov_b32 s47, -2
	v_mov_b32_e32 v5, v4
	v_mov_b32_e32 v6, v4
	v_mov_b32_e32 v7, v4
	v_mov_b32_e32 v12, v4
	v_mov_b32_e32 v13, v4
	v_mov_b32_e32 v14, v4
	v_mov_b32_e32 v15, v4
	v_mov_b32_e32 v20, v4
	v_mov_b32_e32 v21, v4
	v_mov_b32_e32 v22, v4
	v_mov_b32_e32 v23, v4
	v_mov_b32_e32 v28, v4
	v_mov_b32_e32 v29, v4
	v_mov_b32_e32 v30, v4
	v_mov_b32_e32 v31, v4
	v_mov_b32_e32 v36, v4
	v_mov_b32_e32 v37, v4
	v_mov_b32_e32 v38, v4
	v_mov_b32_e32 v39, v4
	v_mov_b32_e32 v44, v4
	v_mov_b32_e32 v45, v4
	v_mov_b32_e32 v46, v4
	v_mov_b32_e32 v47, v4
	v_mov_b32_e32 v52, v4
	v_mov_b32_e32 v53, v4
	v_mov_b32_e32 v54, v4
	v_mov_b32_e32 v55, v4
	v_mov_b32_e32 v60, v4
	v_mov_b32_e32 v61, v4
	v_mov_b32_e32 v62, v4
	v_mov_b32_e32 v63, v4
	v_mov_b32_e32 v8, v4
	v_mov_b32_e32 v9, v4
	v_mov_b32_e32 v10, v4
	v_mov_b32_e32 v11, v4
	v_mov_b32_e32 v16, v4
	v_mov_b32_e32 v17, v4
	v_mov_b32_e32 v18, v4
	v_mov_b32_e32 v19, v4
	v_mov_b32_e32 v24, v4
	v_mov_b32_e32 v25, v4
	v_mov_b32_e32 v26, v4
	v_mov_b32_e32 v27, v4
	v_mov_b32_e32 v32, v4
	v_mov_b32_e32 v33, v4
	v_mov_b32_e32 v34, v4
	v_mov_b32_e32 v35, v4
	v_mov_b32_e32 v40, v4
	v_mov_b32_e32 v41, v4
	v_mov_b32_e32 v42, v4
	v_mov_b32_e32 v43, v4
	v_mov_b32_e32 v48, v4
	v_mov_b32_e32 v49, v4
	v_mov_b32_e32 v50, v4
	v_mov_b32_e32 v51, v4
	v_mov_b32_e32 v56, v4
	v_mov_b32_e32 v57, v4
	v_mov_b32_e32 v58, v4
	v_mov_b32_e32 v59, v4
	v_mov_b32_e32 v64, v4
	v_mov_b32_e32 v65, v4
	v_mov_b32_e32 v66, v4
	v_mov_b32_e32 v67, v4
	v_mov_b32_e32 v68, v4
	v_mov_b32_e32 v69, v4
	v_mov_b32_e32 v70, v4
	v_mov_b32_e32 v71, v4
	v_mov_b32_e32 v76, v4
	v_mov_b32_e32 v77, v4
	v_mov_b32_e32 v78, v4
	v_mov_b32_e32 v79, v4
	v_mov_b32_e32 v84, v4
	v_mov_b32_e32 v85, v4
	v_mov_b32_e32 v86, v4
	v_mov_b32_e32 v87, v4
	v_mov_b32_e32 v92, v4
	v_mov_b32_e32 v93, v4
	v_mov_b32_e32 v94, v4
	v_mov_b32_e32 v95, v4
	v_mov_b32_e32 v100, v4
	v_mov_b32_e32 v101, v4
	v_mov_b32_e32 v102, v4
	v_mov_b32_e32 v103, v4
	v_mov_b32_e32 v108, v4
	v_mov_b32_e32 v109, v4
	v_mov_b32_e32 v110, v4
	v_mov_b32_e32 v111, v4
	v_mov_b32_e32 v116, v4
	v_mov_b32_e32 v117, v4
	v_mov_b32_e32 v118, v4
	v_mov_b32_e32 v119, v4
	v_mov_b32_e32 v124, v4
	v_mov_b32_e32 v125, v4
	v_mov_b32_e32 v126, v4
	v_mov_b32_e32 v127, v4
	v_mov_b32_e32 v72, v4
	v_mov_b32_e32 v73, v4
	v_mov_b32_e32 v74, v4
	v_mov_b32_e32 v75, v4
	v_mov_b32_e32 v80, v4
	v_mov_b32_e32 v81, v4
	v_mov_b32_e32 v82, v4
	v_mov_b32_e32 v83, v4
	v_mov_b32_e32 v88, v4
	v_mov_b32_e32 v89, v4
	v_mov_b32_e32 v90, v4
	v_mov_b32_e32 v91, v4
	v_mov_b32_e32 v96, v4
	v_mov_b32_e32 v97, v4
	v_mov_b32_e32 v98, v4
	v_mov_b32_e32 v99, v4
	v_mov_b32_e32 v104, v4
	v_mov_b32_e32 v105, v4
	v_mov_b32_e32 v106, v4
	v_mov_b32_e32 v107, v4
	v_mov_b32_e32 v112, v4
	v_mov_b32_e32 v113, v4
	v_mov_b32_e32 v114, v4
	v_mov_b32_e32 v115, v4
	v_mov_b32_e32 v120, v4
	v_mov_b32_e32 v121, v4
	v_mov_b32_e32 v122, v4
	v_mov_b32_e32 v123, v4
	v_mov_b32_e32 v128, v4
	v_mov_b32_e32 v129, v4
	v_mov_b32_e32 v130, v4
	v_mov_b32_e32 v131, v4
	v_readfirstlane_b32 s98, v151
	s_nop 3
	s_lshr_b32 s98, s98, 8
	s_cmp_lg_u32 s98, 0
	s_cbranch_scc1 .Lprio_skip_758
	s_setprio 1
